# v38 with MLA_SPLIT 60 (chain workgroups run 60 instead of 66 key tiles of their attention unit during the chunk phase)
# baseline (speedup 1.0000x reference)
; __device__ __forceinline__ void rwkvA_phase(const Frame& F, int l) {
;     ...
;     if (split && F.bid < RB_BLOCKS) { mla_unit(F, F.bid & 7, (F.bid >> 3) * 256, 0, MLA_SPLIT, 1, F.bid); __syncthreads(); }
.LBB0_724:
	s_add_i32 s19, s20, 2
	s_min_u32 s1, s19, 59
	s_mul_i32 s8, s16, 0x6400
	s_mov_b32 s18, s17
	s_mov_b32 s17, s0
	s_mul_i32 s0, s1, 0x30000
	s_and_b64 vcc, exec, s[4:5]
	s_add_i32 s21, s8, 0
	s_cbranch_vccnz .LBB0_726
	v_readlane_b32 s24, v253, 22
	s_add_i32 m0, s21, 0x6000
	v_readlane_b32 s25, v253, 23
	v_readlane_b32 s26, v253, 24
	v_readlane_b32 s27, v253, 25
	s_nop 4
	buffer_load_dwordx4 v201, s[24:27], s0 offen lds

; __device__ __forceinline__ void mla_unit(const Frame& F, int h, int q0, int key0, int ntiles, int mode, int su) {
;     ...
;     for (int t = 0; t < ntiles; t += 2) { MLA_STEP(sA, sB, t); MLA_STEP(sB, sA, t + 1); }
.LBB0_733:
	s_mul_i32 s0, s17, 0x5000
	s_add_i32 s0, s0, 0
	s_add_i32 s0, s0, 0x12c00
	v_add_u32_e32 v95, s0, v209
	ds_read_b64_tr_b16 v[76:77], v95
	ds_read_b64_tr_b16 v[78:79], v95 offset:2560
	v_cvt_pk_bf16_f32 v230, v80, v81
	v_cvt_pk_bf16_f32 v231, v82, v184
	v_cvt_pk_bf16_f32 v232, v185, v186
	v_cvt_pk_bf16_f32 v233, v187, v188
	ds_read_b64_tr_b16 v[184:185], v95 offset:128
	ds_read_b64_tr_b16 v[186:187], v95 offset:2688
	ds_read_b64_tr_b16 v[188:189], v95 offset:192
	ds_read_b64_tr_b16 v[190:191], v95 offset:2752
	ds_read_b64_tr_b16 v[220:221], v95 offset:64
	ds_read_b64_tr_b16 v[222:223], v95 offset:2624
	s_waitcnt lgkmcnt(6)
	v_mfma_f32_32x32x16_bf16 v[48:63], v[76:79], v[230:233], v[48:63]
	ds_read_b64_tr_b16 v[244:245], v95 offset:5120
	ds_read_b64_tr_b16 v[246:247], v95 offset:7680
	v_cvt_pk_bf16_f32 v80, v83, v84
	v_cvt_pk_bf16_f32 v81, v85, v86
	v_cvt_pk_bf16_f32 v82, v87, v88
	v_cvt_pk_bf16_f32 v83, v91, v92
	v_cvt_pk_bf16_f32 v64, v64, v65
	v_cvt_pk_bf16_f32 v65, v66, v67
	s_waitcnt lgkmcnt(6)
	v_mfma_f32_32x32x16_bf16 v[16:31], v[184:187], v[230:233], v[16:31]
	ds_read_b64_tr_b16 v[248:249], v95 offset:5184
	ds_read_b64_tr_b16 v[250:251], v95 offset:7744
	v_cvt_pk_bf16_f32 v66, v89, v90
	v_cvt_pk_bf16_f32 v67, v93, v94
	v_cvt_pk_bf16_f32 v68, v68, v69
	v_cvt_pk_bf16_f32 v69, v70, v71
	v_cvt_pk_bf16_f32 v70, v72, v73
	v_cvt_pk_bf16_f32 v71, v74, v75
	s_waitcnt lgkmcnt(6)
	v_mfma_f32_32x32x16_bf16 v[0:15], v[188:191], v[230:233], v[0:15]
	ds_read_b64_tr_b16 v[76:77], v95 offset:5248
	ds_read_b64_tr_b16 v[78:79], v95 offset:7808
	s_min_u32 s8, s20, 56
	s_add_i32 s8, s8, 3
	s_mul_i32 s9, s17, 0x6400
	s_mul_i32 s1, s8, 0x30000
	s_add_i32 s9, s9, 0
	s_and_b64 vcc, exec, s[4:5]
	s_waitcnt lgkmcnt(6)
	v_mfma_f32_32x32x16_bf16 v[32:47], v[220:223], v[230:233], v[32:47]
	ds_read_b64_tr_b16 v[184:185], v95 offset:5312
	ds_read_b64_tr_b16 v[186:187], v95 offset:7872
	s_waitcnt lgkmcnt(6)
	v_mfma_f32_32x32x16_bf16 v[48:63], v[244:247], v[80:83], v[48:63]
	ds_read_b64_tr_b16 v[188:189], v95 offset:10240
	ds_read_b64_tr_b16 v[190:191], v95 offset:12800
	s_waitcnt lgkmcnt(6)
	v_mfma_f32_32x32x16_bf16 v[32:47], v[248:251], v[80:83], v[32:47]
	ds_read_b64_tr_b16 v[220:221], v95 offset:10304
	ds_read_b64_tr_b16 v[222:223], v95 offset:12864
	s_waitcnt lgkmcnt(6)
	v_mfma_f32_32x32x16_bf16 v[16:31], v[76:79], v[80:83], v[16:31]
	ds_read_b64_tr_b16 v[244:245], v95 offset:10368
	ds_read_b64_tr_b16 v[246:247], v95 offset:12928
	s_waitcnt lgkmcnt(6)
	v_mfma_f32_32x32x16_bf16 v[0:15], v[184:187], v[80:83], v[0:15]
	ds_read_b64_tr_b16 v[248:249], v95 offset:10432
	ds_read_b64_tr_b16 v[250:251], v95 offset:12992
	s_waitcnt lgkmcnt(6)
	v_mfma_f32_32x32x16_bf16 v[48:63], v[188:191], v[64:67], v[48:63]
	ds_read_b64_tr_b16 v[76:77], v95 offset:15360
	ds_read_b64_tr_b16 v[78:79], v95 offset:17920
	s_waitcnt lgkmcnt(6)
	v_mfma_f32_32x32x16_bf16 v[32:47], v[220:223], v[64:67], v[32:47]
	ds_read_b64_tr_b16 v[184:185], v95 offset:15424
	ds_read_b64_tr_b16 v[186:187], v95 offset:17984
	s_waitcnt lgkmcnt(6)
	v_mfma_f32_32x32x16_bf16 v[16:31], v[244:247], v[64:67], v[16:31]
	ds_read_b64_tr_b16 v[188:189], v95 offset:15488
	ds_read_b64_tr_b16 v[190:191], v95 offset:18048
	s_waitcnt lgkmcnt(6)
	v_mfma_f32_32x32x16_bf16 v[0:15], v[248:251], v[64:67], v[0:15]
	ds_read_b64_tr_b16 v[220:221], v95 offset:15552
	ds_read_b64_tr_b16 v[222:223], v95 offset:18112
	s_waitcnt lgkmcnt(6)
	v_mfma_f32_32x32x16_bf16 v[48:63], v[76:79], v[68:71], v[48:63]
	s_waitcnt lgkmcnt(4)
	v_mfma_f32_32x32x16_bf16 v[32:47], v[184:187], v[68:71], v[32:47]
	s_waitcnt vmcnt(0)
	s_waitcnt lgkmcnt(0)
	s_barrier
	v_mfma_f32_32x32x16_bf16 v[16:31], v[188:191], v[68:71], v[16:31]
	s_waitcnt lgkmcnt(0)
	v_mfma_f32_32x32x16_bf16 v[0:15], v[220:223], v[68:71], v[0:15]
	s_cbranch_vccz .LBB0_738
	s_and_b64 vcc, exec, s[6:7]
	s_lshl_b32 s8, s8, 17
	s_cbranch_vccnz .LBB0_736

; __device__ __forceinline__ void mla_unit(const Frame& F, int h, int q0, int key0, int ntiles, int mode, int su) {
;     ...
;     for (int t = 0; t < ntiles; t += 2) { MLA_STEP(sA, sB, t); MLA_STEP(sB, sA, t + 1); }
.LBB0_742:
	s_mul_i32 s0, s18, 0x5000
	v_add_u32_e32 v127, s0, v210
	ds_read_b64_tr_b16 v[108:109], v127
	ds_read_b64_tr_b16 v[110:111], v127 offset:2560
	v_cvt_pk_bf16_f32 v230, v112, v113
	v_cvt_pk_bf16_f32 v231, v114, v184
	v_cvt_pk_bf16_f32 v232, v185, v186
	v_cvt_pk_bf16_f32 v233, v187, v188
	ds_read_b64_tr_b16 v[184:185], v127 offset:128
	ds_read_b64_tr_b16 v[186:187], v127 offset:2688
	ds_read_b64_tr_b16 v[188:189], v127 offset:192
	ds_read_b64_tr_b16 v[190:191], v127 offset:2752
	ds_read_b64_tr_b16 v[220:221], v127 offset:64
	ds_read_b64_tr_b16 v[222:223], v127 offset:2624
	s_waitcnt lgkmcnt(6)
	v_mfma_f32_32x32x16_bf16 v[48:63], v[108:111], v[230:233], v[48:63]
	ds_read_b64_tr_b16 v[244:245], v127 offset:5120
	ds_read_b64_tr_b16 v[246:247], v127 offset:7680
	v_cvt_pk_bf16_f32 v112, v115, v116
	v_cvt_pk_bf16_f32 v113, v117, v118
	v_cvt_pk_bf16_f32 v114, v119, v120
	v_cvt_pk_bf16_f32 v115, v123, v124
	v_cvt_pk_bf16_f32 v96, v96, v97
	v_cvt_pk_bf16_f32 v97, v98, v99
	s_waitcnt lgkmcnt(6)
	v_mfma_f32_32x32x16_bf16 v[16:31], v[184:187], v[230:233], v[16:31]
	ds_read_b64_tr_b16 v[248:249], v127 offset:5184
	ds_read_b64_tr_b16 v[250:251], v127 offset:7744
	v_cvt_pk_bf16_f32 v98, v121, v122
	v_cvt_pk_bf16_f32 v99, v125, v126
	v_cvt_pk_bf16_f32 v100, v100, v101
	v_cvt_pk_bf16_f32 v101, v102, v103
	v_cvt_pk_bf16_f32 v102, v104, v105
	v_cvt_pk_bf16_f32 v103, v106, v107
	s_waitcnt lgkmcnt(6)
	v_mfma_f32_32x32x16_bf16 v[0:15], v[188:191], v[230:233], v[0:15]
	ds_read_b64_tr_b16 v[108:109], v127 offset:5248
	ds_read_b64_tr_b16 v[110:111], v127 offset:7808
	s_cmp_lt_u32 s20, 58
	s_waitcnt lgkmcnt(6)
	v_mfma_f32_32x32x16_bf16 v[32:47], v[220:223], v[230:233], v[32:47]
	ds_read_b64_tr_b16 v[184:185], v127 offset:5312
	ds_read_b64_tr_b16 v[186:187], v127 offset:7872
	s_waitcnt lgkmcnt(6)
	v_mfma_f32_32x32x16_bf16 v[48:63], v[244:247], v[112:115], v[48:63]
	ds_read_b64_tr_b16 v[188:189], v127 offset:10240
	ds_read_b64_tr_b16 v[190:191], v127 offset:12800
	s_waitcnt lgkmcnt(6)
	v_mfma_f32_32x32x16_bf16 v[32:47], v[248:251], v[112:115], v[32:47]
	ds_read_b64_tr_b16 v[220:221], v127 offset:10304
	ds_read_b64_tr_b16 v[222:223], v127 offset:12864
	s_waitcnt lgkmcnt(6)
	v_mfma_f32_32x32x16_bf16 v[16:31], v[108:111], v[112:115], v[16:31]
	ds_read_b64_tr_b16 v[244:245], v127 offset:10368
	ds_read_b64_tr_b16 v[246:247], v127 offset:12928
	s_waitcnt lgkmcnt(6)
	v_mfma_f32_32x32x16_bf16 v[0:15], v[184:187], v[112:115], v[0:15]
	ds_read_b64_tr_b16 v[248:249], v127 offset:10432
	ds_read_b64_tr_b16 v[250:251], v127 offset:12992
	s_waitcnt lgkmcnt(6)
	v_mfma_f32_32x32x16_bf16 v[48:63], v[188:191], v[96:99], v[48:63]
	ds_read_b64_tr_b16 v[108:109], v127 offset:15360
	ds_read_b64_tr_b16 v[110:111], v127 offset:17920
	s_waitcnt lgkmcnt(6)
	v_mfma_f32_32x32x16_bf16 v[32:47], v[220:223], v[96:99], v[32:47]
	ds_read_b64_tr_b16 v[184:185], v127 offset:15424
	ds_read_b64_tr_b16 v[186:187], v127 offset:17984
	s_waitcnt lgkmcnt(6)
	v_mfma_f32_32x32x16_bf16 v[16:31], v[244:247], v[96:99], v[16:31]
	ds_read_b64_tr_b16 v[188:189], v127 offset:15488
	ds_read_b64_tr_b16 v[190:191], v127 offset:18048
	s_waitcnt lgkmcnt(6)
	v_mfma_f32_32x32x16_bf16 v[0:15], v[248:251], v[96:99], v[0:15]
	ds_read_b64_tr_b16 v[220:221], v127 offset:15552
	ds_read_b64_tr_b16 v[222:223], v127 offset:18112
	s_waitcnt lgkmcnt(6)
	v_mfma_f32_32x32x16_bf16 v[48:63], v[108:111], v[100:103], v[48:63]
	s_waitcnt lgkmcnt(4)
	v_mfma_f32_32x32x16_bf16 v[32:47], v[184:187], v[100:103], v[32:47]
	s_waitcnt vmcnt(0)
	s_waitcnt lgkmcnt(0)
	s_barrier
	v_mfma_f32_32x32x16_bf16 v[16:31], v[188:191], v[100:103], v[16:31]
	s_waitcnt lgkmcnt(0)
	v_mfma_f32_32x32x16_bf16 v[0:15], v[220:223], v[100:103], v[0:15]
	s_cbranch_scc0 .LBB0_744
	s_mov_b32 s0, s16
	s_mov_b32 s16, s18
	s_mov_b32 s20, s19
	s_branch .LBB0_724

; __device__ __forceinline__ void mla_unit(const Frame& F, int h, int q0, int key0, int ntiles, int mode, int su) {
;     ...
;     unsigned ko[4], vo[3];
; #pragma unroll
;     for (int i = 0; i < 4; ++i) { const int sl = ((i < 3) ? (F.wave + 8 * i) : 24) * 64 + F.lane, key = sl / 25, part = sl - key * 25;
;         ko[i] = (unsigned)((key0 + key) * 1536 + h * 192 + ((part < 24) ? part : 0) * 8) * 2u; }
; #pragma unroll
;     for (int i = 0; i < 3; ++i) { const int sl = ((i < 2) ? (F.wave + 8 * i) : (16 + (F.wave & 3))) * 64 + F.lane, key = sl / 20, part = sl - key * 20;
;         vo[i] = (unsigned)((key0 + key) * 1024 + h * 128 + ((part < 16) ? part : 0) * 8) * 2u; }
;     const __amdgpu_buffer_rsrc_t rK = __builtin_amdgcn_make_buffer_rsrc((void*)KC, 0, 0x7ffffff0, 0x00020000), rV = __builtin_amdgcn_make_buffer_rsrc((void*)VC, 0, 0x7ffffff0, 0x00020000);
;     ...
;     __syncthreads();
;     MLA_DMA(0, 0); MLA_DMA(1, 1);
.LBB0_876:
	s_mov_b64 s[8:9], s[80:81]
	v_readlane_b32 s16, v253, 22
	s_add_u32 s16, s8, 0x4fbe4000
	s_mov_b32 s11, 0x51eb851f
	s_addc_u32 s7, s9, 0
	v_mul_hi_i32 v102, v130, s11
	s_and_b64 s[2:3], s[0:1], exec
	v_lshrrev_b32_e32 v120, 31, v102
	v_ashrrev_i32_e32 v102, 3, v102
	s_cselect_b32 s6, 0xf00, 0
	v_add_u32_e32 v102, v102, v120
	s_movk_i32 s12, 0xffe7
	v_mad_u64_u32 v[138:139], s[2:3], v102, s12, v[130:131]
	v_add_u32_e32 v102, s6, v102
	s_movk_i32 s10, 0x600
	v_mul_lo_u32 v102, v102, s10
	v_cmp_gt_i32_e32 vcc, 24, v138
	v_lshlrev_b32_e32 v120, 3, v138
	v_add_u32_e32 v102, s5, v102
	v_cndmask_b32_e32 v120, 0, v120, vcc
	v_add_lshl_u32 v201, v102, v120, 1
	v_add_u32_e32 v102, 0x200, v130
	v_mul_hi_i32 v120, v102, s11
	v_lshrrev_b32_e32 v127, 31, v120
	v_ashrrev_i32_e32 v120, 3, v120
	v_add_u32_e32 v120, v120, v127
	v_mad_u64_u32 v[138:139], s[2:3], v120, s12, v[102:103]
	v_add_u32_e32 v120, s6, v120
	v_mul_lo_u32 v120, v120, s10
	v_cmp_gt_i32_e32 vcc, 24, v138
	v_lshlrev_b32_e32 v127, 3, v138
	v_add_u32_e32 v120, s5, v120
	v_cndmask_b32_e32 v127, 0, v127, vcc
	v_add_lshl_u32 v203, v120, v127, 1
	v_add_u32_e32 v120, 0x400, v130
	v_mul_hi_i32 v127, v120, s11
	v_lshrrev_b32_e32 v138, 31, v127
	v_ashrrev_i32_e32 v127, 3, v127
	v_add_u32_e32 v127, v127, v138
	v_mad_u64_u32 v[138:139], s[2:3], v127, s12, v[120:121]
	v_add_u32_e32 v120, s6, v127
	v_mul_lo_u32 v120, v120, s10
	v_cmp_gt_i32_e32 vcc, 24, v138
	v_lshlrev_b32_e32 v127, 3, v138
	v_add_u32_e32 v120, s5, v120
	v_cndmask_b32_e32 v127, 0, v127, vcc
	v_add_lshl_u32 v205, v120, v127, 1
	v_add_u32_e32 v120, 0x600, v198
	v_mul_hi_i32 v127, v120, s11
	v_lshrrev_b32_e32 v138, 31, v127
	v_ashrrev_i32_e32 v127, 3, v127
	v_add_u32_e32 v127, v127, v138
	v_mad_u64_u32 v[138:139], s[2:3], v127, s12, v[120:121]
	v_add_u32_e32 v120, s6, v127
	v_readlane_b32 s17, v253, 23
	v_mul_lo_u32 v120, v120, s10
	s_lshl_b32 s10, s82, 10
	s_and_b32 s17, s7, 0xffff
	s_add_i32 s7, s10, 0
	v_readlane_b32 s18, v253, 24
	v_readlane_b32 s19, v253, 25
	s_mov_b32 m0, s7
	s_waitcnt lgkmcnt(0)
	s_barrier
	v_cmp_gt_i32_e32 vcc, 24, v138
	s_nop 0
	buffer_load_dwordx4 v201, s[16:19], 0 offen lds
	s_add_i32 m0, s7, 0x2000
	v_lshlrev_b32_e32 v127, 3, v138
	buffer_load_dwordx4 v203, s[16:19], 0 offen lds
	s_add_i32 m0, s7, 0x4000
	v_cndmask_b32_e32 v127, 0, v127, vcc
	buffer_load_dwordx4 v205, s[16:19], 0 offen lds
	v_add_u32_e32 v127, s5, v127
	s_cmp_eq_u32 s82, 0
	v_add_lshl_u32 v207, v127, v120, 1
	s_cselect_b64 s[2:3], -1, 0
	s_cmp_lg_u32 s82, 0
	s_cbranch_scc1 .LBB0_878
	s_add_i32 m0, 0, 0x6000
	s_nop 0
	buffer_load_dwordx4 v207, s[16:19], 0 offen lds

; __device__ __forceinline__ void unpack8(const u32x4 w, float (&f)[8]) { f[0] = bflo(w.x); f[1] = bfhi(w.x); f[2] = bflo(w.y); f[3] = bfhi(w.y); f[4] = bflo(w.z); f[5] = bfhi(w.z); f[6] = bflo(w.w); f[7] = bfhi(w.w); }
; __device__ __forceinline__ u32x4 pack8(const float (&f)[8]) { u32x4 w; w.x = cvt_pk_bf16(f[0], f[1]); w.y = cvt_pk_bf16(f[2], f[3]); w.z = cvt_pk_bf16(f[4], f[5]); w.w = cvt_pk_bf16(f[6], f[7]); return w; }
; __device__ __forceinline__ void lds_barrier() { asm volatile("s_waitcnt lgkmcnt(0)\n\ts_barrier" ::: "memory"); }
; __device__ __forceinline__ void mla_unit(const Frame& F, int h, int q0, int key0, int ntiles, int mode, int su) {
;     ...
;     bf16x8 Qf[12];
;     {
;         const bf16_t* qp = Q + (size_t)qr * 1536 + h * QHD;
; #pragma unroll
;         for (int ks = 0; ks < 8; ++ks) { float x[8]; unpack8(*(const u32x4*)(qp + 16 * ks + 8 * hh), x);
; #pragma unroll
;             for (int j = 0; j < 8; ++j) x[j] *= SC;
;             Qf[ks] = __builtin_bit_cast(bf16x8, pack8(x)); }
; #pragma unroll
;         for (int ks = 8; ks < 12; ++ks) {
;             const int d0 = 16 * ks + 8 * hh;
;             const u32x4 own = *(const u32x4*)(qp + d0);
;             if (qr < SEQ) {
;                 const u32x4 par = *(const u32x4*)(qp + d0 + ((ks & 1) ? -16 : 16));
;                 float xo[8], xp[8], o[8]; unpack8(own, xo); unpack8(par, xp);
;                 const float* rp = rope + ((size_t)qr * 32 + ((ks - 8) >> 1) * 16 + 8 * hh) * 2;
; #pragma unroll
;                 for (int j = 0; j < 8; ++j) { const float cs = rp[2 * j], sn = rp[2 * j + 1]; o[j] = SC * ((ks & 1) ? (xp[j] * sn + xo[j] * cs) : (xo[j] * cs - xp[j] * sn)); }
;                 Qf[ks] = __builtin_bit_cast(bf16x8, pack8(o));
;             } else { float x[8]; unpack8(own, x);
; #pragma unroll
;                 for (int j = 0; j < 8; ++j) x[j] *= SC;
;                 Qf[ks] = __builtin_bit_cast(bf16x8, pack8(x)); }
;         }
;     }
;     ...
;     __syncthreads();
;     MLA_DMA(0, 0); MLA_DMA(1, 1);
;     asm volatile("s_waitcnt vmcnt(0)" ::: "memory");
;     lds_barrier();
.LBB0_884:
	s_mov_b32 s14, 0x3dd53b94
	v_pk_mul_f32 v[96:97], v[96:97], s[14:15] op_sel_hi:[1,0]
	v_pk_mul_f32 v[98:99], v[98:99], s[14:15] op_sel_hi:[1,0]
	v_cvt_pk_bf16_f32 v145, v96, v97
	v_pk_mul_f32 v[96:97], v[106:107], s[14:15] op_sel_hi:[1,0]
	v_cvt_pk_bf16_f32 v146, v98, v99
	v_cvt_pk_bf16_f32 v150, v96, v97
	v_lshlrev_b32_e32 v96, 16, v92
	v_and_b32_e32 v97, 0xffff0000, v92
	v_lshlrev_b32_e32 v92, 16, v93
	v_and_b32_e32 v93, 0xffff0000, v93
	v_pk_mul_f32 v[92:93], v[92:93], s[14:15] op_sel_hi:[1,0]
	v_pk_mul_f32 v[98:99], v[104:105], s[14:15] op_sel_hi:[1,0]
	v_cvt_pk_bf16_f32 v153, v92, v93
	v_lshlrev_b32_e32 v92, 16, v88
	v_and_b32_e32 v93, 0xffff0000, v88
	v_lshlrev_b32_e32 v88, 16, v89
	v_and_b32_e32 v89, 0xffff0000, v89
	v_pk_mul_f32 v[88:89], v[88:89], s[14:15] op_sel_hi:[1,0]
	v_cvt_pk_bf16_f32 v149, v98, v99
	v_cvt_pk_bf16_f32 v157, v88, v89
	v_lshlrev_b32_e32 v88, 16, v84
	v_and_b32_e32 v89, 0xffff0000, v84
	v_lshlrev_b32_e32 v84, 16, v85
	v_and_b32_e32 v85, 0xffff0000, v85
	v_pk_mul_f32 v[84:85], v[84:85], s[14:15] op_sel_hi:[1,0]
	v_lshlrev_b32_e32 v98, 16, v94
	v_and_b32_e32 v99, 0xffff0000, v94
	v_lshlrev_b32_e32 v94, 16, v95
	v_and_b32_e32 v95, 0xffff0000, v95
	v_cvt_pk_bf16_f32 v161, v84, v85
	v_lshlrev_b32_e32 v84, 16, v80
	v_and_b32_e32 v85, 0xffff0000, v80
	v_lshlrev_b32_e32 v80, 16, v81
	v_and_b32_e32 v81, 0xffff0000, v81
	v_pk_mul_f32 v[94:95], v[94:95], s[14:15] op_sel_hi:[1,0]
	v_pk_mul_f32 v[80:81], v[80:81], s[14:15] op_sel_hi:[1,0]
	v_cvt_pk_bf16_f32 v155, v94, v95
	v_lshlrev_b32_e32 v94, 16, v90
	v_and_b32_e32 v95, 0xffff0000, v90
	v_lshlrev_b32_e32 v90, 16, v91
	v_and_b32_e32 v91, 0xffff0000, v91
	v_cvt_pk_bf16_f32 v165, v80, v81
	v_lshlrev_b32_e32 v80, 16, v76
	v_and_b32_e32 v81, 0xffff0000, v76
	v_lshlrev_b32_e32 v76, 16, v77
	v_and_b32_e32 v77, 0xffff0000, v77
	v_pk_mul_f32 v[90:91], v[90:91], s[14:15] op_sel_hi:[1,0]
	v_pk_mul_f32 v[76:77], v[76:77], s[14:15] op_sel_hi:[1,0]
	v_cvt_pk_bf16_f32 v159, v90, v91
	v_lshlrev_b32_e32 v90, 16, v86
	v_and_b32_e32 v91, 0xffff0000, v86
	v_lshlrev_b32_e32 v86, 16, v87
	v_and_b32_e32 v87, 0xffff0000, v87
	v_cvt_pk_bf16_f32 v169, v76, v77
	v_lshlrev_b32_e32 v76, 16, v72
	v_and_b32_e32 v77, 0xffff0000, v72
	v_lshlrev_b32_e32 v72, 16, v73
	v_and_b32_e32 v73, 0xffff0000, v73
	v_pk_mul_f32 v[86:87], v[86:87], s[14:15] op_sel_hi:[1,0]
	v_pk_mul_f32 v[72:73], v[72:73], s[14:15] op_sel_hi:[1,0]
	v_cvt_pk_bf16_f32 v163, v86, v87
	v_lshlrev_b32_e32 v86, 16, v82
	v_and_b32_e32 v87, 0xffff0000, v82
	v_lshlrev_b32_e32 v82, 16, v83
	v_and_b32_e32 v83, 0xffff0000, v83
	v_cvt_pk_bf16_f32 v173, v72, v73
	v_lshlrev_b32_e32 v72, 16, v68
	v_and_b32_e32 v73, 0xffff0000, v68
	v_lshlrev_b32_e32 v68, 16, v69
	v_and_b32_e32 v69, 0xffff0000, v69
	v_pk_mul_f32 v[82:83], v[82:83], s[14:15] op_sel_hi:[1,0]
	v_pk_mul_f32 v[68:69], v[68:69], s[14:15] op_sel_hi:[1,0]
	v_cvt_pk_bf16_f32 v167, v82, v83
	v_lshlrev_b32_e32 v82, 16, v78
	v_and_b32_e32 v83, 0xffff0000, v78
	v_lshlrev_b32_e32 v78, 16, v79
	v_and_b32_e32 v79, 0xffff0000, v79
	v_cvt_pk_bf16_f32 v177, v68, v69
	v_lshlrev_b32_e32 v68, 16, v64
	v_and_b32_e32 v69, 0xffff0000, v64
	v_lshlrev_b32_e32 v64, 16, v65
	v_and_b32_e32 v65, 0xffff0000, v65
	v_mul_f32_e32 v102, 0x3dd53b94, v121
	s_and_b64 s[8:9], s[0:1], exec
	v_pk_mul_f32 v[78:79], v[78:79], s[14:15] op_sel_hi:[1,0]
	v_pk_mul_f32 v[64:65], v[64:65], s[14:15] op_sel_hi:[1,0]
	v_cvt_pk_bf16_f32 v139, v140, v102
	v_mul_f32_e32 v102, 0x3dd53b94, v113
	v_cvt_pk_bf16_f32 v171, v78, v79
	v_lshlrev_b32_e32 v78, 16, v74
	v_and_b32_e32 v79, 0xffff0000, v74
	v_lshlrev_b32_e32 v74, 16, v75
	v_and_b32_e32 v75, 0xffff0000, v75
	v_cvt_pk_bf16_f32 v181, v64, v65
	v_lshlrev_b32_e32 v64, 4, v131
	s_movk_i32 s8, 0x190
	v_cvt_pk_bf16_f32 v143, v126, v102
	v_mul_f32_e32 v102, 0x3dd53b94, v103
	v_pk_mul_f32 v[74:75], v[74:75], s[14:15] op_sel_hi:[1,0]
	s_waitcnt vmcnt(0)
	v_mad_u32_u24 v212, v129, s8, v64
	v_cvt_pk_bf16_f32 v147, v112, v102
	v_pk_mul_f32 v[100:101], v[100:101], s[14:15] op_sel_hi:[1,0]
	v_mul_f32_e32 v102, 0x3dd53b94, v109
	v_pk_mul_f32 v[98:99], v[98:99], s[14:15] op_sel_hi:[1,0]
	v_cvt_pk_bf16_f32 v175, v74, v75
	v_lshlrev_b32_e32 v74, 16, v70
	v_and_b32_e32 v75, 0xffff0000, v70
	v_lshlrev_b32_e32 v70, 16, v71
	v_and_b32_e32 v71, 0xffff0000, v71
	s_waitcnt lgkmcnt(0)
	s_barrier
; #define LAS __attribute__((address_space(3)))
; #define MFMA32(a, b, c) __builtin_amdgcn_mfma_f32_32x32x16_bf16(a, b, c, 0, 0, 0)
; __device__ __forceinline__ void mla_unit(const Frame& F, int h, int q0, int key0, int ntiles, int mode, int su) {
;     ...
;     const int krd = ql * MA_KSTR + 16 * hh;
;     const int vrd = (4 * hh + ((F.lane & 15) >> 2)) * MA_VSTR + (((F.lane >> 4) & 1) * 16 + (F.lane & 3) * 4) * 2;
;     f32x16 sA[2], sB[2];
;     {   const LAS unsigned char* kb = F.lds + MA_K_OFF + krd;
; #pragma unroll
;         for (int kt = 0; kt < 2; ++kt) { { const float nm = -m;
; #pragma unroll
;             for (int r = 0; r < 16; ++r) sA[kt][r] = nm; }
; #pragma unroll
;             for (int ks = 0; ks < 12; ++ks) { const bf16x8 kf = *(const LAS bf16x8*)(kb + kt * 32 * MA_KSTR + ks * 32); sA[kt] = MFMA32(kf, Qf[ks], sA[kt]); } } }
;     int c0 = 0, c1 = 1, c2 = 2;
; __device__ __forceinline__ void attn_phase(const Frame& F, int l, int flags) {
;     ...
;         { const int u = F.bid; if (u < 256) { const bool rs = (u < RB_BLOCKS) && (F.nb == 256);
;             mla_unit(F, u & 7, (u >> 3) * 256, rs ? 64 * MLA_SPLIT : 0, rs ? MROWS / 64 - MLA_SPLIT : MROWS / 64, rs ? 2 : 0, u); } }
	v_add_u32_e32 v213, 0, v212
	v_cvt_pk_bf16_f32 v148, v100, v101
	v_cvt_pk_bf16_f32 v151, v108, v102
	v_pk_mul_f32 v[96:97], v[96:97], s[14:15] op_sel_hi:[1,0]
	v_cvt_pk_bf16_f32 v154, v98, v99
	v_pk_mul_f32 v[70:71], v[70:71], s[14:15] op_sel_hi:[1,0]
	v_lshlrev_b32_e32 v204, 2, v131
	v_lshrrev_b32_e32 v64, 2, v198
	ds_read_b128 v[98:101], v213
	ds_read_b128 v[102:105], v213 offset:32
	v_cvt_pk_bf16_f32 v152, v96, v97
	v_cvt_pk_bf16_f32 v179, v70, v71
	v_lshlrev_b32_e32 v70, 16, v66
	v_and_b32_e32 v71, 0xffff0000, v66
	v_lshlrev_b32_e32 v66, 16, v67
	v_and_b32_e32 v67, 0xffff0000, v67
	v_and_or_b32 v96, v64, 3, v204
	v_and_b32_e32 v64, 16, v198
	v_lshlrev_b32_e32 v65, 2, v198
	v_pk_mul_f32 v[76:77], v[76:77], s[14:15] op_sel_hi:[1,0]
	v_pk_mul_f32 v[78:79], v[78:79], s[14:15] op_sel_hi:[1,0]
	v_pk_mul_f32 v[72:73], v[72:73], s[14:15] op_sel_hi:[1,0]
	v_pk_mul_f32 v[74:75], v[74:75], s[14:15] op_sel_hi:[1,0]
	v_pk_mul_f32 v[68:69], v[68:69], s[14:15] op_sel_hi:[1,0]
	v_pk_mul_f32 v[70:71], v[70:71], s[14:15] op_sel_hi:[1,0]
	v_pk_mul_f32 v[66:67], v[66:67], s[14:15] op_sel_hi:[1,0]
	v_and_or_b32 v97, v65, 12, v64
	s_waitcnt vmcnt(0)
	v_xor_b32_e32 v64, 0x80000000, v199
	v_pk_mul_f32 v[92:93], v[92:93], s[14:15] op_sel_hi:[1,0]
	v_pk_mul_f32 v[94:95], v[94:95], s[14:15] op_sel_hi:[1,0]
	v_pk_mul_f32 v[88:89], v[88:89], s[14:15] op_sel_hi:[1,0]
	v_pk_mul_f32 v[90:91], v[90:91], s[14:15] op_sel_hi:[1,0]
	v_pk_mul_f32 v[84:85], v[84:85], s[14:15] op_sel_hi:[1,0]
	v_pk_mul_f32 v[86:87], v[86:87], s[14:15] op_sel_hi:[1,0]
	v_pk_mul_f32 v[80:81], v[80:81], s[14:15] op_sel_hi:[1,0]
	v_pk_mul_f32 v[82:83], v[82:83], s[14:15] op_sel_hi:[1,0]
	v_cvt_pk_bf16_f32 v172, v76, v77
	v_cvt_pk_bf16_f32 v174, v78, v79
	v_cvt_pk_bf16_f32 v176, v72, v73
	v_cvt_pk_bf16_f32 v178, v74, v75
	v_cvt_pk_bf16_f32 v180, v68, v69
	v_cvt_pk_bf16_f32 v182, v70, v71
	v_cvt_pk_bf16_f32 v183, v66, v67
	v_mov_b32_e32 v65, v64
	v_mov_b32_e32 v66, v64
	v_mov_b32_e32 v67, v64
	v_mov_b32_e32 v68, v64
	v_mov_b32_e32 v69, v64
	v_mov_b32_e32 v70, v64
	v_mov_b32_e32 v71, v64
	v_mov_b32_e32 v72, v64
	v_mov_b32_e32 v73, v64
	v_mov_b32_e32 v74, v64
	v_mov_b32_e32 v75, v64
	v_mov_b32_e32 v76, v64
	v_mov_b32_e32 v77, v64
	v_mov_b32_e32 v78, v64
	v_mov_b32_e32 v79, v64
	v_cvt_pk_bf16_f32 v156, v92, v93
	v_cvt_pk_bf16_f32 v158, v94, v95
	v_cvt_pk_bf16_f32 v160, v88, v89
	v_cvt_pk_bf16_f32 v162, v90, v91
	v_cvt_pk_bf16_f32 v164, v84, v85
	v_cvt_pk_bf16_f32 v166, v86, v87
	v_cvt_pk_bf16_f32 v168, v80, v81
	v_cvt_pk_bf16_f32 v170, v82, v83
	s_waitcnt lgkmcnt(1)
	v_mfma_f32_32x32x16_bf16 v[80:95], v[98:101], v[152:155], v[64:79]
	ds_read_b128 v[98:101], v213 offset:64
	v_mul_f32_e64 v110, v110, s14
	v_mul_f32_e64 v111, v111, s14
	v_mul_f32_e64 v116, v116, s14
	v_mul_f32_e64 v117, v117, s14
	v_cvt_pk_bf16_f32 v144, v110, v111
	v_pk_mul_f32 v[114:115], v[114:115], s[14:15] op_sel_hi:[1,0]
	v_pk_mul_f32 v[136:137], v[136:137], s[14:15] op_sel_hi:[1,0]
	v_cvt_pk_bf16_f32 v138, v116, v117
	s_waitcnt lgkmcnt(1)
	v_mfma_f32_32x32x16_bf16 v[80:95], v[102:105], v[156:159], v[80:95]
	v_cvt_pk_bf16_f32 v136, v136, v137
	v_cvt_pk_bf16_f32 v137, v114, v115
	v_mul_f32_e64 v114, v124, s14
	v_mul_f32_e64 v115, v125, s14
	v_mul_f32_e64 v116, v122, s14
	v_mul_f32_e64 v117, v123, s14
	v_pk_mul_f32 v[118:119], v[118:119], s[14:15] op_sel_hi:[1,0]
	v_cvt_pk_bf16_f32 v141, v116, v117
	v_cvt_pk_bf16_f32 v140, v118, v119
	s_waitcnt lgkmcnt(0)
	v_mfma_f32_32x32x16_bf16 v[80:95], v[98:101], v[160:163], v[80:95]
	ds_read_b128 v[98:101], v213 offset:96
	v_cvt_pk_bf16_f32 v142, v114, v115
	s_movk_i32 s8, 0x140
	s_movk_i32 s3, 0x48
	v_mul_lo_u32 v96, v96, s8
	s_cselect_b32 s3, s3, 0x84
	v_lshl_or_b32 v216, v97, 1, v96
	s_waitcnt lgkmcnt(0)
	v_mfma_f32_32x32x16_bf16 v[80:95], v[98:101], v[164:167], v[80:95]
	ds_read_b128 v[98:101], v213 offset:128
	s_add_i32 s8, 0, 0x12c00
	v_cndmask_b32_e64 v96, 0, -1, s[0:1]
	s_mov_b32 s16, 2
	s_mov_b32 s17, 1
	s_add_i32 s18, s3, -1
	v_add_u32_e32 v229, s8, v216
	s_waitcnt lgkmcnt(0)
	v_mfma_f32_32x32x16_bf16 v[80:95], v[98:101], v[168:171], v[80:95]
	ds_read_b128 v[98:101], v213 offset:160
	s_mov_b32 s0, 0
	v_readfirstlane_b32 s19, v96
	s_mov_b32 s24, 0
	s_waitcnt lgkmcnt(0)
	v_mfma_f32_32x32x16_bf16 v[80:95], v[98:101], v[172:175], v[80:95]
	ds_read_b128 v[98:101], v213 offset:192
	s_waitcnt lgkmcnt(0)
	v_mfma_f32_32x32x16_bf16 v[80:95], v[98:101], v[176:179], v[80:95]
	ds_read_b128 v[98:101], v213 offset:224
	s_waitcnt lgkmcnt(0)
	v_mfma_f32_32x32x16_bf16 v[80:95], v[98:101], v[180:183], v[80:95]
	ds_read_b128 v[98:101], v213 offset:256
	s_waitcnt lgkmcnt(0)
	v_mfma_f32_32x32x16_bf16 v[80:95], v[98:101], v[148:151], v[80:95]
	ds_read_b128 v[98:101], v213 offset:288
	s_waitcnt lgkmcnt(0)
	v_mfma_f32_32x32x16_bf16 v[80:95], v[98:101], v[144:147], v[80:95]
	ds_read_b128 v[98:101], v213 offset:320
	s_waitcnt lgkmcnt(0)
	v_mfma_f32_32x32x16_bf16 v[80:95], v[98:101], v[140:143], v[80:95]
	ds_read_b128 v[98:101], v213 offset:352
	s_waitcnt lgkmcnt(0)
	v_mfma_f32_32x32x16_bf16 v[80:95], v[98:101], v[136:139], v[80:95]
	ds_read_b128 v[98:101], v213 offset:12800
	s_waitcnt lgkmcnt(0)
	v_mfma_f32_32x32x16_bf16 v[64:79], v[98:101], v[152:155], v[64:79]
	ds_read_b128 v[98:101], v213 offset:12832
	s_waitcnt lgkmcnt(0)
	v_mfma_f32_32x32x16_bf16 v[64:79], v[98:101], v[156:159], v[64:79]
	ds_read_b128 v[98:101], v213 offset:12864
	s_waitcnt lgkmcnt(0)
	v_mfma_f32_32x32x16_bf16 v[64:79], v[98:101], v[160:163], v[64:79]
	ds_read_b128 v[98:101], v213 offset:12896
	s_waitcnt lgkmcnt(0)
	v_mfma_f32_32x32x16_bf16 v[64:79], v[98:101], v[164:167], v[64:79]
	ds_read_b128 v[98:101], v213 offset:12928
	s_waitcnt lgkmcnt(0)
	v_mfma_f32_32x32x16_bf16 v[64:79], v[98:101], v[168:171], v[64:79]
	ds_read_b128 v[98:101], v213 offset:12960
	s_waitcnt lgkmcnt(0)
	v_mfma_f32_32x32x16_bf16 v[64:79], v[98:101], v[172:175], v[64:79]
	ds_read_b128 v[98:101], v213 offset:12992
	s_waitcnt lgkmcnt(0)
	v_mfma_f32_32x32x16_bf16 v[64:79], v[98:101], v[176:179], v[64:79]
	ds_read_b128 v[98:101], v213 offset:13024
	s_waitcnt lgkmcnt(0)
	v_mfma_f32_32x32x16_bf16 v[64:79], v[98:101], v[180:183], v[64:79]
	ds_read_b128 v[98:101], v213 offset:13056
	s_waitcnt lgkmcnt(0)
	v_mfma_f32_32x32x16_bf16 v[64:79], v[98:101], v[148:151], v[64:79]
	ds_read_b128 v[98:101], v213 offset:13088
	s_waitcnt lgkmcnt(0)
	v_mfma_f32_32x32x16_bf16 v[64:79], v[98:101], v[144:147], v[64:79]
	ds_read_b128 v[98:101], v213 offset:13120
	s_waitcnt lgkmcnt(0)
	v_mfma_f32_32x32x16_bf16 v[64:79], v[98:101], v[140:143], v[64:79]
	ds_read_b128 v[98:101], v213 offset:13152
	s_waitcnt lgkmcnt(0)
	v_mfma_f32_32x32x16_bf16 v[64:79], v[98:101], v[136:139], v[64:79]
